# relative-position-bias table build spread over workgroups 0..6 (one pass each) instead of 7 serial passes on workgroup 0
# baseline (speedup 1.0000x reference)
; #define INP(i) ((const float*)LDP(i))
; __global__ void __launch_bounds__(NWAVES * 64, 2) mk_fwd(Args a) {
;     ...
;                 if (bx == 0) for (int idx = tid; idx < 24 * 129; idx += NWAVES * 64) {
;                     const int gh = idx / 129, jk = idx % 129, gi = gh / 8, dil = gi == 0 ? 1 : (gi == 1 ? 4 : 16), rel = (jk - 64) * dil, n = rel < 0 ? -rel : rel;
;                     int bucket = rel > 0 ? 16 : 0;
;                     if (n < 8) bucket += n; else { int large = 8 + (int)(logf((float)n / 8.0f) / logf(128.0f) * 8.0f); if (large > 15) large = 15; bucket += large; }
;                     biasrel[idx] = INP(2)[bucket * 24 + gh] * LOG2E; }
.LBB0_353:
	v_readlane_b32 s0, v252, 63
	s_nop 3
	s_lshl_b32 s0, s0, 9
	s_nop 0
	v_add_u32_e32 v66, s0, v66
	s_movk_i32 s0, 0xc18
	v_cmp_gt_i32_e32 vcc, s0, v66
	s_nop 1
	s_and_saveexec_b64 s[0:1], vcc
	s_cbranch_execz .LBB0_360
	v_readlane_b32 s2, v254, 33
	v_ashrrev_i32_e32 v67, 31, v66
	v_readlane_b32 s3, v254, 34
	s_nop 1
	v_lshl_add_u64 v[0:1], v[66:67], 2, s[2:3]
	s_mov_b64 s[2:3], 0x104000
	v_lshl_add_u64 v[0:1], v[0:1], 0, s[2:3]
	s_mov_b64 s[2:3], 0
	s_branch .LBB0_356
.LBB0_355:
	s_or_b64 exec, exec, s[10:11]
	ds_read_b64 v[6:7], v236 offset:16
	ds_read_b64 v[8:9], v236 offset:16
	s_mov_b32 s10, s97
	v_mad_u64_u32 v[2:3], s[12:13], v4, 24, v[2:3]
	s_waitcnt lgkmcnt(0)
	v_readfirstlane_b32 s11, v7
	s_waitcnt lgkmcnt(0)
	v_readfirstlane_b32 s96, v8
	s_or_b64 s[10:11], s[96:97], s[10:11]
	v_ashrrev_i32_e32 v3, 31, v2
	v_lshl_add_u64 v[2:3], v[2:3], 2, s[10:11]
	global_load_dword v2, v[2:3], off
	s_movk_i32 s5, 0x8000
	v_cmp_lt_i32_e32 vcc, s5, v66
	s_or_b64 s[2:3], vcc, s[2:3]
	v_add_u32_e32 v66, 0x200, v66
	s_waitcnt vmcnt(0)
	v_mul_f32_e32 v2, 0x3fb8aa3b, v2
	global_store_dword v[0:1], v2, off
	v_lshl_add_u64 v[0:1], v[0:1], 0, s[68:69]
	s_andn2_b64 exec, exec, s[2:3]
	s_cbranch_execz .LBB0_360
